# residual GEMM epilogues: the eight row-sum atomics of a unit issued together at the end (partial sums parked in spare VGPRs) so in-epilogue counted waits do not retire atomics
# baseline (speedup 1.0000x reference)
; __device__ __forceinline__ unsigned cvtpk(float lo, float hi) { f32x2 v = {lo, hi}; bf16x2_t b = __builtin_convertvector(v, bf16x2_t); return __builtin_bit_cast(unsigned, b); }
; #define SWZ_XOR(v, m) __uint_as_float((unsigned)__builtin_amdgcn_ds_swizzle((int)__float_as_uint(v), ((m) << 10) | 0x1f))
; __device__ __forceinline__ float sum32x(float v) { auto rr = __builtin_amdgcn_permlane32_swap(__float_as_uint(v), __float_as_uint(v), false, false); return __uint_as_float(rr[0]) + __uint_as_float(rr[1]); }
;     __device__ __forceinline__ void operator()(const pg8::f32x4 (&acc)[2][2][4][2], const pg8::Unit& u, int wr, int wc, int fr, int fq) const {
;     ...
;         } else if (kind == EK_RES) {
; #pragma unroll
;             for (int ai = 0; ai < 2; ++ai) {
;                 pg8::f32x4 pre[4][2][2];
; #pragma unroll
;                 for (int m = 0; m < 4; ++m) {
;                     const size_t ro = (size_t)(rowb + 128 * ai + 16 * m) * ldc + colb;
; #pragma unroll
;                     for (int bj = 0; bj < 2; ++bj)
; #pragma unroll
;                         for (int n = 0; n < 2; ++n) pre[m][bj][n] = *(const pg8::f32x4*)(fin + ro + 128 * bj + NS * n);
;                 }
; #pragma unroll
;                 for (int m = 0; m < 4; ++m) {
;                     const size_t ro = (size_t)(rowb + 128 * ai + 16 * m) * ldc + colb;
;                     float ssr = 0.f;
; #pragma unroll
;                     for (int bj = 0; bj < 2; ++bj)
; #pragma unroll
;                         for (int n = 0; n < 2; ++n) {
;                             const size_t off = ro + 128 * bj + NS * n;
;                             const pg8::f32x4 v = pre[m][bj][n] + acc[ai][bj][m][n] * coef;
;                             *(pg8::f32x4*)(fout + off) = v;
;                             if (flags & 2) { u32x2 w; w.x = cvtpk(v[0], v[1]); w.y = cvtpk(v[2], v[3]); *(u32x2*)(o0 + off) = w; ssr += (v[0] * v[0] + v[1] * v[1]) + (v[2] * v[2] + v[3] * v[3]); }
;                         }
;                     if (flags & 2) { ssr += SWZ_XOR(ssr, 16); ssr = sum32x(ssr); if (fq == 0) atomicAdd((float*)o1 + (rowb + 128 * ai + 16 * m), ssr); }
;                 }
.LBB0_1068:
	s_andn2_b64 vcc, exec, s[8:9]
	s_cbranch_vccnz .LBB0_1118
	v_ashrrev_i32_e32 v231, 31, v230
	v_or_b32_e32 v64, 16, v228
	v_lshl_add_u64 v[234:235], v[230:231], 2, v[136:137]
	v_mad_i64_i32 v[140:141], s[8:9], v65, v228, 0
	v_mad_i64_i32 v[240:241], s[8:9], v65, v64, 0
	v_or_b32_e32 v64, 32, v228
	v_lshl_add_u64 v[140:141], v[140:141], 2, v[234:235]
	v_mad_i64_i32 v[238:239], s[8:9], v65, v64, 0
	v_or_b32_e32 v64, 48, v228
	global_load_dword v66, v215, s[40:41] offset:1040
	global_load_dwordx4 v[204:207], v[140:141], off
	global_load_dwordx4 v[196:199], v[140:141], off offset:16
	global_load_dwordx4 v[188:191], v[140:141], off offset:528
	global_load_dwordx4 v[192:195], v[140:141], off offset:512
	v_lshl_add_u64 v[140:141], v[240:241], 2, v[234:235]
	v_mad_i64_i32 v[236:237], s[8:9], v65, v64, 0
	global_load_dwordx4 v[180:183], v[140:141], off offset:16
	global_load_dwordx4 v[184:187], v[140:141], off
	global_load_dwordx4 v[172:175], v[140:141], off offset:528
	global_load_dwordx4 v[176:179], v[140:141], off offset:512
	v_lshl_add_u64 v[140:141], v[238:239], 2, v[234:235]
	v_lshl_add_u64 v[144:145], v[236:237], 2, v[234:235]
	global_load_dwordx4 v[164:167], v[140:141], off offset:16
	global_load_dwordx4 v[168:171], v[140:141], off
	global_load_dwordx4 v[156:159], v[140:141], off offset:528
	global_load_dwordx4 v[160:163], v[140:141], off offset:512
	global_load_dwordx4 v[148:151], v[144:145], off offset:16
	global_load_dwordx4 v[152:155], v[144:145], off
	s_nop 0
	global_load_dwordx4 v[140:143], v[144:145], off offset:528
	s_nop 0
	global_load_dwordx4 v[144:147], v[144:145], off offset:512
	v_and_b32_e32 v64, 2, v67
	v_cmp_ne_u32_e64 s[10:11], 0, v64
	v_mad_i64_i32 v[202:203], s[18:19], v65, v228, v[230:231]
	v_ashrrev_i32_e32 v229, 31, v228
	s_mov_b64 s[8:9], -1
	v_lshl_add_u64 v[242:243], v[202:203], 2, v[138:139]
	s_and_b64 vcc, exec, s[10:11]
	s_waitcnt vmcnt(16)
	v_mov_b32_e32 v232, v66
	v_mov_b32_e32 v233, v66
	s_waitcnt vmcnt(15)
	v_pk_fma_f32 v[212:213], v[134:135], v[66:67], v[206:207] op_sel_hi:[1,0,1]
	v_pk_fma_f32 v[210:211], v[132:133], v[66:67], v[204:205] op_sel_hi:[1,0,1]
	s_waitcnt vmcnt(14)
	v_pk_fma_f32 v[208:209], v[128:129], v[232:233], v[196:197]
	s_waitcnt vmcnt(12)
	v_pk_fma_f32 v[204:205], v[124:125], v[232:233], v[192:193]
	v_pk_fma_f32 v[200:201], v[120:121], v[232:233], v[188:189]
	global_store_dwordx4 v[242:243], v[210:213], off
	s_cbranch_vccz .LBB0_1073
	v_mul_f32_e32 v64, v211, v211
	v_mul_f32_e32 v67, v213, v213
	v_fmac_f32_e32 v64, v210, v210
	v_fmac_f32_e32 v67, v212, v212
	v_add_f32_e32 v64, v64, v67
	v_mov_b32_e32 v67, v66
	v_cvt_pk_bf16_f32 v188, v210, v211
	v_cvt_pk_bf16_f32 v189, v212, v213
	v_lshl_add_u64 v[192:193], v[202:203], 1, v[68:69]
	v_pk_fma_f32 v[210:211], v[130:131], v[66:67], v[198:199]
	global_store_dwordx2 v[192:193], v[188:189], off
	v_cvt_pk_bf16_f32 v188, v208, v209
	v_cvt_pk_bf16_f32 v189, v210, v211
	global_store_dwordx4 v[242:243], v[208:211], off offset:16
	global_store_dwordx2 v[192:193], v[188:189], off offset:8
	v_mul_f32_e32 v188, v209, v209
	v_mul_f32_e32 v189, v211, v211
	v_fmac_f32_e32 v188, v208, v208
	v_fmac_f32_e32 v189, v210, v210
	v_add_f32_e32 v188, v188, v189
	v_pk_fma_f32 v[206:207], v[126:127], v[66:67], v[194:195]
	v_add_f32_e32 v64, v64, v188
	v_cvt_pk_bf16_f32 v188, v204, v205
	v_cvt_pk_bf16_f32 v189, v206, v207
	global_store_dwordx4 v[242:243], v[204:207], off offset:512
	global_store_dwordx2 v[192:193], v[188:189], off offset:256
	v_mul_f32_e32 v188, v205, v205
	v_mul_f32_e32 v189, v207, v207
	v_fmac_f32_e32 v188, v204, v204
	v_fmac_f32_e32 v189, v206, v206
	v_add_f32_e32 v188, v188, v189
	v_pk_fma_f32 v[202:203], v[122:123], v[66:67], v[190:191]
	v_add_f32_e32 v64, v188, v64
	v_mul_f32_e32 v67, v201, v201
	v_mul_f32_e32 v188, v203, v203
	v_fmac_f32_e32 v67, v200, v200
	v_fmac_f32_e32 v188, v202, v202
	v_add_f32_e32 v67, v67, v188
	v_add_f32_e32 v64, v67, v64
	ds_swizzle_b32 v67, v64 offset:swizzle(SWAP,16)
	v_cvt_pk_bf16_f32 v188, v200, v201
	v_cvt_pk_bf16_f32 v189, v202, v203
	global_store_dwordx4 v[242:243], v[200:203], off offset:528
	global_store_dwordx2 v[192:193], v[188:189], off offset:264
	s_waitcnt lgkmcnt(0)
	v_add_f32_e32 v64, v64, v67
	v_mov_b32_e32 v67, v64
	s_nop 1
	v_permlane32_swap_b32_e32 v64, v67
	s_and_saveexec_b64 s[8:9], s[4:5]
	s_cbranch_execz .LBB0_1072
	v_lshl_add_u64 v[188:189], v[228:229], 2, v[70:71]
	v_add_f32_e32 v64, v64, v67
	v_mov_b32_e32 v217, v64

; __device__ __forceinline__ unsigned cvtpk(float lo, float hi) { f32x2 v = {lo, hi}; bf16x2_t b = __builtin_convertvector(v, bf16x2_t); return __builtin_bit_cast(unsigned, b); }
; #define SWZ_XOR(v, m) __uint_as_float((unsigned)__builtin_amdgcn_ds_swizzle((int)__float_as_uint(v), ((m) << 10) | 0x1f))
; __device__ __forceinline__ float sum32x(float v) { auto rr = __builtin_amdgcn_permlane32_swap(__float_as_uint(v), __float_as_uint(v), false, false); return __uint_as_float(rr[0]) + __uint_as_float(rr[1]); }
;     __device__ __forceinline__ void operator()(const pg8::f32x4 (&acc)[2][2][4][2], const pg8::Unit& u, int wr, int wc, int fr, int fq) const {
;     ...
;                 for (int m = 0; m < 4; ++m) {
;                     const size_t ro = (size_t)(rowb + 128 * ai + 16 * m) * ldc + colb;
;                     float ssr = 0.f;
; #pragma unroll
;                     for (int bj = 0; bj < 2; ++bj)
; #pragma unroll
;                         for (int n = 0; n < 2; ++n) {
;                             const size_t off = ro + 128 * bj + NS * n;
;                             const pg8::f32x4 v = pre[m][bj][n] + acc[ai][bj][m][n] * coef;
;                             *(pg8::f32x4*)(fout + off) = v;
;                             if (flags & 2) { u32x2 w; w.x = cvtpk(v[0], v[1]); w.y = cvtpk(v[2], v[3]); *(u32x2*)(o0 + off) = w; ssr += (v[0] * v[0] + v[1] * v[1]) + (v[2] * v[2] + v[3] * v[3]); }
;                         }
;                     if (flags & 2) { ssr += SWZ_XOR(ssr, 16); ssr = sum32x(ssr); if (fq == 0) atomicAdd((float*)o1 + (rowb + 128 * ai + 16 * m), ssr); }
;                 }
.LBB0_1075:
	v_lshl_add_u64 v[190:191], v[240:241], 0, v[230:231]
	v_mov_b32_e32 v67, v66
	v_cndmask_b32_e64 v64, 0, 1, s[10:11]
	s_waitcnt vmcnt(11)
	v_pk_fma_f32 v[196:197], v[118:119], v[66:67], v[186:187]
	v_pk_fma_f32 v[194:195], v[116:117], v[232:233], v[184:185]
	v_lshl_add_u64 v[198:199], v[190:191], 2, v[138:139]
	s_mov_b64 s[48:49], -1
	v_cmp_ne_u32_e64 s[8:9], 1, v64
	s_andn2_b64 vcc, exec, s[10:11]
	v_pk_fma_f32 v[192:193], v[108:109], v[232:233], v[180:181]
	s_waitcnt vmcnt(9)
	v_pk_fma_f32 v[188:189], v[112:113], v[232:233], v[176:177]
	v_pk_fma_f32 v[184:185], v[104:105], v[232:233], v[172:173]
	global_store_dwordx4 v[198:199], v[194:197], off
	s_cbranch_vccnz .LBB0_1079
	v_cvt_pk_bf16_f32 v172, v194, v195
	v_cvt_pk_bf16_f32 v173, v196, v197
	v_lshl_add_u64 v[176:177], v[190:191], 1, v[68:69]
	global_store_dwordx2 v[176:177], v[172:173], off
	v_mul_f32_e32 v64, v195, v195
	v_mul_f32_e32 v172, v197, v197
	v_fmac_f32_e32 v64, v194, v194
	v_fmac_f32_e32 v172, v196, v196
	v_pk_fma_f32 v[194:195], v[110:111], v[66:67], v[182:183]
	v_add_f32_e32 v64, v64, v172
	v_cvt_pk_bf16_f32 v172, v192, v193
	v_cvt_pk_bf16_f32 v173, v194, v195
	global_store_dwordx4 v[198:199], v[192:195], off offset:16
	global_store_dwordx2 v[176:177], v[172:173], off offset:8
	v_mul_f32_e32 v172, v193, v193
	v_mul_f32_e32 v173, v195, v195
	v_fmac_f32_e32 v172, v192, v192
	v_fmac_f32_e32 v173, v194, v194
	v_add_f32_e32 v172, v172, v173
	v_pk_fma_f32 v[190:191], v[114:115], v[66:67], v[178:179]
	v_add_f32_e32 v64, v64, v172
	v_cvt_pk_bf16_f32 v172, v188, v189
	v_cvt_pk_bf16_f32 v173, v190, v191
	global_store_dwordx4 v[198:199], v[188:191], off offset:512
	global_store_dwordx2 v[176:177], v[172:173], off offset:256
	v_mul_f32_e32 v172, v189, v189
	v_mul_f32_e32 v173, v191, v191
	v_fmac_f32_e32 v172, v188, v188
	v_fmac_f32_e32 v173, v190, v190
	v_add_f32_e32 v172, v172, v173
	v_pk_fma_f32 v[186:187], v[106:107], v[66:67], v[174:175]
	v_add_f32_e32 v64, v64, v172
	v_mul_f32_e32 v67, v185, v185
	v_mul_f32_e32 v172, v187, v187
	v_fmac_f32_e32 v67, v184, v184
	v_fmac_f32_e32 v172, v186, v186
	v_add_f32_e32 v67, v67, v172
	v_add_f32_e32 v64, v64, v67
	ds_swizzle_b32 v67, v64 offset:swizzle(SWAP,16)
	v_cvt_pk_bf16_f32 v172, v184, v185
	v_cvt_pk_bf16_f32 v173, v186, v187
	global_store_dwordx4 v[198:199], v[184:187], off offset:528
	global_store_dwordx2 v[176:177], v[172:173], off offset:264
	s_waitcnt lgkmcnt(0)
	v_add_f32_e32 v64, v64, v67
	v_mov_b32_e32 v67, v64
	s_nop 1
	v_permlane32_swap_b32_e32 v64, v67
	s_and_saveexec_b64 s[10:11], s[4:5]
	s_cbranch_execz .LBB0_1078
	v_lshl_add_u64 v[172:173], v[228:229], 2, v[70:71]
	v_add_f32_e32 v64, v64, v67
	v_mov_b32_e32 v219, v64

; __device__ __forceinline__ unsigned cvtpk(float lo, float hi) { f32x2 v = {lo, hi}; bf16x2_t b = __builtin_convertvector(v, bf16x2_t); return __builtin_bit_cast(unsigned, b); }
; #define SWZ_XOR(v, m) __uint_as_float((unsigned)__builtin_amdgcn_ds_swizzle((int)__float_as_uint(v), ((m) << 10) | 0x1f))
; __device__ __forceinline__ float sum32x(float v) { auto rr = __builtin_amdgcn_permlane32_swap(__float_as_uint(v), __float_as_uint(v), false, false); return __uint_as_float(rr[0]) + __uint_as_float(rr[1]); }
;     __device__ __forceinline__ void operator()(const pg8::f32x4 (&acc)[2][2][4][2], const pg8::Unit& u, int wr, int wc, int fr, int fq) const {
;     ...
;                 for (int m = 0; m < 4; ++m) {
;                     const size_t ro = (size_t)(rowb + 128 * ai + 16 * m) * ldc + colb;
;                     float ssr = 0.f;
; #pragma unroll
;                     for (int bj = 0; bj < 2; ++bj)
; #pragma unroll
;                         for (int n = 0; n < 2; ++n) {
;                             const size_t off = ro + 128 * bj + NS * n;
;                             const pg8::f32x4 v = pre[m][bj][n] + acc[ai][bj][m][n] * coef;
;                             *(pg8::f32x4*)(fout + off) = v;
;                             if (flags & 2) { u32x2 w; w.x = cvtpk(v[0], v[1]); w.y = cvtpk(v[2], v[3]); *(u32x2*)(o0 + off) = w; ssr += (v[0] * v[0] + v[1] * v[1]) + (v[2] * v[2] + v[3] * v[3]); }
;                         }
;                     if (flags & 2) { ssr += SWZ_XOR(ssr, 16); ssr = sum32x(ssr); if (fq == 0) atomicAdd((float*)o1 + (rowb + 128 * ai + 16 * m), ssr); }
;                 }
.LBB0_1081:
	v_lshl_add_u64 v[174:175], v[238:239], 0, v[230:231]
	v_mov_b32_e32 v67, v66
	s_waitcnt vmcnt(8)
	v_pk_fma_f32 v[180:181], v[102:103], v[66:67], v[170:171]
	v_pk_fma_f32 v[178:179], v[100:101], v[232:233], v[168:169]
	v_lshl_add_u64 v[182:183], v[174:175], 2, v[138:139]
	s_mov_b64 s[10:11], -1
	s_and_b64 vcc, exec, s[8:9]
	v_pk_fma_f32 v[176:177], v[92:93], v[232:233], v[164:165]
	s_waitcnt vmcnt(6)
	v_pk_fma_f32 v[172:173], v[96:97], v[232:233], v[160:161]
	v_pk_fma_f32 v[168:169], v[88:89], v[232:233], v[156:157]
	global_store_dwordx4 v[182:183], v[178:181], off
	s_cbranch_vccnz .LBB0_1085
	v_cvt_pk_bf16_f32 v156, v178, v179
	v_cvt_pk_bf16_f32 v157, v180, v181
	v_lshl_add_u64 v[160:161], v[174:175], 1, v[68:69]
	global_store_dwordx2 v[160:161], v[156:157], off
	v_mul_f32_e32 v64, v179, v179
	v_mul_f32_e32 v156, v181, v181
	v_fmac_f32_e32 v64, v178, v178
	v_fmac_f32_e32 v156, v180, v180
	v_pk_fma_f32 v[178:179], v[94:95], v[66:67], v[166:167]
	v_add_f32_e32 v64, v64, v156
	v_cvt_pk_bf16_f32 v156, v176, v177
	v_cvt_pk_bf16_f32 v157, v178, v179
	global_store_dwordx4 v[182:183], v[176:179], off offset:16
	global_store_dwordx2 v[160:161], v[156:157], off offset:8
	v_mul_f32_e32 v156, v177, v177
	v_mul_f32_e32 v157, v179, v179
	v_fmac_f32_e32 v156, v176, v176
	v_fmac_f32_e32 v157, v178, v178
	v_add_f32_e32 v156, v156, v157
	v_pk_fma_f32 v[174:175], v[98:99], v[66:67], v[162:163]
	v_add_f32_e32 v64, v64, v156
	v_cvt_pk_bf16_f32 v156, v172, v173
	v_cvt_pk_bf16_f32 v157, v174, v175
	global_store_dwordx4 v[182:183], v[172:175], off offset:512
	global_store_dwordx2 v[160:161], v[156:157], off offset:256
	v_mul_f32_e32 v156, v173, v173
	v_mul_f32_e32 v157, v175, v175
	v_fmac_f32_e32 v156, v172, v172
	v_fmac_f32_e32 v157, v174, v174
	v_add_f32_e32 v156, v156, v157
	v_pk_fma_f32 v[170:171], v[90:91], v[66:67], v[158:159]
	v_add_f32_e32 v64, v64, v156
	v_mul_f32_e32 v67, v169, v169
	v_mul_f32_e32 v156, v171, v171
	v_fmac_f32_e32 v67, v168, v168
	v_fmac_f32_e32 v156, v170, v170
	v_add_f32_e32 v67, v67, v156
	v_add_f32_e32 v64, v64, v67
	ds_swizzle_b32 v67, v64 offset:swizzle(SWAP,16)
	v_cvt_pk_bf16_f32 v156, v168, v169
	v_cvt_pk_bf16_f32 v157, v170, v171
	global_store_dwordx4 v[182:183], v[168:171], off offset:528
	global_store_dwordx2 v[160:161], v[156:157], off offset:264
	s_waitcnt lgkmcnt(0)
	v_add_f32_e32 v64, v64, v67
	v_mov_b32_e32 v67, v64
	s_nop 1
	v_permlane32_swap_b32_e32 v64, v67
	s_and_saveexec_b64 s[10:11], s[4:5]
	s_cbranch_execz .LBB0_1084
	v_lshl_add_u64 v[156:157], v[228:229], 2, v[70:71]
	v_add_f32_e32 v64, v64, v67
	v_mov_b32_e32 v221, v64

; __device__ __forceinline__ unsigned cvtpk(float lo, float hi) { f32x2 v = {lo, hi}; bf16x2_t b = __builtin_convertvector(v, bf16x2_t); return __builtin_bit_cast(unsigned, b); }
; #define SWZ_XOR(v, m) __uint_as_float((unsigned)__builtin_amdgcn_ds_swizzle((int)__float_as_uint(v), ((m) << 10) | 0x1f))
; __device__ __forceinline__ float sum32x(float v) { auto rr = __builtin_amdgcn_permlane32_swap(__float_as_uint(v), __float_as_uint(v), false, false); return __uint_as_float(rr[0]) + __uint_as_float(rr[1]); }
;     __device__ __forceinline__ void operator()(const pg8::f32x4 (&acc)[2][2][4][2], const pg8::Unit& u, int wr, int wc, int fr, int fq) const {
;     ...
;                 for (int m = 0; m < 4; ++m) {
;                     const size_t ro = (size_t)(rowb + 128 * ai + 16 * m) * ldc + colb;
;                     float ssr = 0.f;
; #pragma unroll
;                     for (int bj = 0; bj < 2; ++bj)
; #pragma unroll
;                         for (int n = 0; n < 2; ++n) {
;                             const size_t off = ro + 128 * bj + NS * n;
;                             const pg8::f32x4 v = pre[m][bj][n] + acc[ai][bj][m][n] * coef;
;                             *(pg8::f32x4*)(fout + off) = v;
;                             if (flags & 2) { u32x2 w; w.x = cvtpk(v[0], v[1]); w.y = cvtpk(v[2], v[3]); *(u32x2*)(o0 + off) = w; ssr += (v[0] * v[0] + v[1] * v[1]) + (v[2] * v[2] + v[3] * v[3]); }
;                         }
;                     if (flags & 2) { ssr += SWZ_XOR(ssr, 16); ssr = sum32x(ssr); if (fq == 0) atomicAdd((float*)o1 + (rowb + 128 * ai + 16 * m), ssr); }
;                 }
.LBB0_1087:
	v_lshl_add_u64 v[158:159], v[236:237], 0, v[230:231]
	v_mov_b32_e32 v67, v66
	s_waitcnt vmcnt(5)
	v_pk_fma_f32 v[164:165], v[86:87], v[66:67], v[154:155]
	v_pk_fma_f32 v[162:163], v[84:85], v[232:233], v[152:153]
	v_lshl_add_u64 v[166:167], v[158:159], 2, v[138:139]
	s_mov_b64 s[10:11], -1
	s_and_b64 vcc, exec, s[8:9]
	v_pk_fma_f32 v[160:161], v[76:77], v[232:233], v[148:149]
	s_waitcnt vmcnt(3)
	v_pk_fma_f32 v[156:157], v[80:81], v[232:233], v[144:145]
	v_pk_fma_f32 v[152:153], v[72:73], v[232:233], v[140:141]
	global_store_dwordx4 v[166:167], v[162:165], off
	s_cbranch_vccnz .LBB0_1091
	v_cvt_pk_bf16_f32 v140, v162, v163
	v_cvt_pk_bf16_f32 v141, v164, v165
	v_lshl_add_u64 v[144:145], v[158:159], 1, v[68:69]
	global_store_dwordx2 v[144:145], v[140:141], off
	v_mul_f32_e32 v64, v163, v163
	v_mul_f32_e32 v140, v165, v165
	v_fmac_f32_e32 v64, v162, v162
	v_fmac_f32_e32 v140, v164, v164
	v_pk_fma_f32 v[162:163], v[78:79], v[66:67], v[150:151]
	v_add_f32_e32 v64, v64, v140
	v_cvt_pk_bf16_f32 v140, v160, v161
	v_cvt_pk_bf16_f32 v141, v162, v163
	global_store_dwordx4 v[166:167], v[160:163], off offset:16
	global_store_dwordx2 v[144:145], v[140:141], off offset:8
	v_mul_f32_e32 v140, v161, v161
	v_mul_f32_e32 v141, v163, v163
	v_fmac_f32_e32 v140, v160, v160
	v_fmac_f32_e32 v141, v162, v162
	v_add_f32_e32 v140, v140, v141
	v_pk_fma_f32 v[158:159], v[82:83], v[66:67], v[146:147]
	v_add_f32_e32 v64, v64, v140
	v_cvt_pk_bf16_f32 v140, v156, v157
	v_cvt_pk_bf16_f32 v141, v158, v159
	global_store_dwordx4 v[166:167], v[156:159], off offset:512
	global_store_dwordx2 v[144:145], v[140:141], off offset:256
	v_mul_f32_e32 v140, v157, v157
	v_mul_f32_e32 v141, v159, v159
	v_fmac_f32_e32 v140, v156, v156
	v_fmac_f32_e32 v141, v158, v158
	v_add_f32_e32 v140, v140, v141
	v_pk_fma_f32 v[154:155], v[74:75], v[66:67], v[142:143]
	v_add_f32_e32 v64, v64, v140
	v_mul_f32_e32 v67, v153, v153
	v_mul_f32_e32 v140, v155, v155
	v_fmac_f32_e32 v67, v152, v152
	v_fmac_f32_e32 v140, v154, v154
	v_add_f32_e32 v67, v67, v140
	v_add_f32_e32 v64, v64, v67
	ds_swizzle_b32 v67, v64 offset:swizzle(SWAP,16)
	v_cvt_pk_bf16_f32 v140, v152, v153
	v_cvt_pk_bf16_f32 v141, v154, v155
	global_store_dwordx4 v[166:167], v[152:155], off offset:528
	global_store_dwordx2 v[144:145], v[140:141], off offset:264
	s_waitcnt lgkmcnt(0)
	v_add_f32_e32 v64, v64, v67
	v_mov_b32_e32 v67, v64
	s_nop 1
	v_permlane32_swap_b32_e32 v64, v67
	s_and_saveexec_b64 s[10:11], s[4:5]
	s_cbranch_execz .LBB0_1090
	v_lshl_add_u64 v[140:141], v[228:229], 2, v[70:71]
	v_add_f32_e32 v64, v64, v67
	v_mov_b32_e32 v223, v64

; __device__ __forceinline__ unsigned cvtpk(float lo, float hi) { f32x2 v = {lo, hi}; bf16x2_t b = __builtin_convertvector(v, bf16x2_t); return __builtin_bit_cast(unsigned, b); }
; #define SWZ_XOR(v, m) __uint_as_float((unsigned)__builtin_amdgcn_ds_swizzle((int)__float_as_uint(v), ((m) << 10) | 0x1f))
; __device__ __forceinline__ float sum32x(float v) { auto rr = __builtin_amdgcn_permlane32_swap(__float_as_uint(v), __float_as_uint(v), false, false); return __uint_as_float(rr[0]) + __uint_as_float(rr[1]); }
;     __device__ __forceinline__ void operator()(const pg8::f32x4 (&acc)[2][2][4][2], const pg8::Unit& u, int wr, int wc, int fr, int fq) const {
;     ...
;             for (int ai = 0; ai < 2; ++ai) {
;                 pg8::f32x4 pre[4][2][2];
; #pragma unroll
;                 for (int m = 0; m < 4; ++m) {
;                     const size_t ro = (size_t)(rowb + 128 * ai + 16 * m) * ldc + colb;
; #pragma unroll
;                     for (int bj = 0; bj < 2; ++bj)
; #pragma unroll
;                         for (int n = 0; n < 2; ++n) pre[m][bj][n] = *(const pg8::f32x4*)(fin + ro + 128 * bj + NS * n);
;                 }
; #pragma unroll
;                 for (int m = 0; m < 4; ++m) {
;                     const size_t ro = (size_t)(rowb + 128 * ai + 16 * m) * ldc + colb;
;                     float ssr = 0.f;
; #pragma unroll
;                     for (int bj = 0; bj < 2; ++bj)
; #pragma unroll
;                         for (int n = 0; n < 2; ++n) {
;                             const size_t off = ro + 128 * bj + NS * n;
;                             const pg8::f32x4 v = pre[m][bj][n] + acc[ai][bj][m][n] * coef;
;                             *(pg8::f32x4*)(fout + off) = v;
;                             if (flags & 2) { u32x2 w; w.x = cvtpk(v[0], v[1]); w.y = cvtpk(v[2], v[3]); *(u32x2*)(o0 + off) = w; ssr += (v[0] * v[0] + v[1] * v[1]) + (v[2] * v[2] + v[3] * v[3]); }
;                         }
;                     if (flags & 2) { ssr += SWZ_XOR(ssr, 16); ssr = sum32x(ssr); if (fq == 0) atomicAdd((float*)o1 + (rowb + 128 * ai + 16 * m), ssr); }
;                 }
.LBB0_1093:
	v_add_u32_e32 v64, 0x80, v228
	v_add_u32_e32 v67, 0x90, v228
	v_mad_i64_i32 v[140:141], s[10:11], v65, v64, 0
	v_mad_i64_i32 v[240:241], s[10:11], v65, v67, 0
	v_add_u32_e32 v67, 0xa0, v228
	v_lshl_add_u64 v[140:141], v[140:141], 2, v[234:235]
	v_mad_i64_i32 v[238:239], s[10:11], v65, v67, 0
	v_add_u32_e32 v67, 0xb0, v228
	global_load_dwordx4 v[204:207], v[140:141], off
	global_load_dwordx4 v[196:199], v[140:141], off offset:16
	global_load_dwordx4 v[188:191], v[140:141], off offset:528
	global_load_dwordx4 v[192:195], v[140:141], off offset:512
	v_lshl_add_u64 v[140:141], v[240:241], 2, v[234:235]
	v_mad_i64_i32 v[236:237], s[10:11], v65, v67, 0
	global_load_dwordx4 v[180:183], v[140:141], off offset:16
	global_load_dwordx4 v[184:187], v[140:141], off
	global_load_dwordx4 v[172:175], v[140:141], off offset:528
	global_load_dwordx4 v[176:179], v[140:141], off offset:512
	v_lshl_add_u64 v[140:141], v[238:239], 2, v[234:235]
	v_lshl_add_u64 v[144:145], v[236:237], 2, v[234:235]
	global_load_dwordx4 v[164:167], v[140:141], off offset:16
	global_load_dwordx4 v[168:171], v[140:141], off
	global_load_dwordx4 v[156:159], v[140:141], off offset:528
	global_load_dwordx4 v[160:163], v[140:141], off offset:512
	global_load_dwordx4 v[148:151], v[144:145], off offset:16
	global_load_dwordx4 v[152:155], v[144:145], off
	s_nop 0
	global_load_dwordx4 v[140:143], v[144:145], off offset:528
	s_nop 0
	global_load_dwordx4 v[144:147], v[144:145], off offset:512
	v_mad_i64_i32 v[202:203], s[10:11], v65, v64, v[230:231]
	v_mov_b32_e32 v67, v66
	v_lshl_add_u64 v[234:235], v[202:203], 2, v[138:139]
	s_mov_b64 s[10:11], -1
	s_and_b64 vcc, exec, s[8:9]
	s_waitcnt vmcnt(15)
	v_pk_fma_f32 v[212:213], v[62:63], v[66:67], v[206:207]
	v_pk_fma_f32 v[210:211], v[60:61], v[232:233], v[204:205]
	s_waitcnt vmcnt(14)
	v_pk_fma_f32 v[208:209], v[52:53], v[232:233], v[196:197]
	s_waitcnt vmcnt(12)
	v_pk_fma_f32 v[204:205], v[56:57], v[232:233], v[192:193]
	v_pk_fma_f32 v[200:201], v[48:49], v[232:233], v[188:189]
	global_store_dwordx4 v[234:235], v[210:213], off
	s_cbranch_vccnz .LBB0_1097
	v_cvt_pk_bf16_f32 v188, v210, v211
	v_cvt_pk_bf16_f32 v189, v212, v213
	v_lshl_add_u64 v[192:193], v[202:203], 1, v[68:69]
	global_store_dwordx2 v[192:193], v[188:189], off
	v_mul_f32_e32 v64, v211, v211
	v_mul_f32_e32 v188, v213, v213
	v_fmac_f32_e32 v64, v210, v210
	v_fmac_f32_e32 v188, v212, v212
	v_pk_fma_f32 v[210:211], v[54:55], v[66:67], v[198:199]
	v_add_f32_e32 v64, v64, v188
	v_cvt_pk_bf16_f32 v188, v208, v209
	v_cvt_pk_bf16_f32 v189, v210, v211
	global_store_dwordx4 v[234:235], v[208:211], off offset:16
	global_store_dwordx2 v[192:193], v[188:189], off offset:8
	v_mul_f32_e32 v188, v209, v209
	v_mul_f32_e32 v189, v211, v211
	v_fmac_f32_e32 v188, v208, v208
	v_fmac_f32_e32 v189, v210, v210
	v_add_f32_e32 v188, v188, v189
	v_pk_fma_f32 v[206:207], v[58:59], v[66:67], v[194:195]
	v_add_f32_e32 v64, v64, v188
	v_cvt_pk_bf16_f32 v188, v204, v205
	v_cvt_pk_bf16_f32 v189, v206, v207
	global_store_dwordx4 v[234:235], v[204:207], off offset:512
	global_store_dwordx2 v[192:193], v[188:189], off offset:256
	v_mul_f32_e32 v188, v205, v205
	v_mul_f32_e32 v189, v207, v207
	v_fmac_f32_e32 v188, v204, v204
	v_fmac_f32_e32 v189, v206, v206
	v_add_f32_e32 v188, v188, v189
	v_pk_fma_f32 v[202:203], v[50:51], v[66:67], v[190:191]
	v_add_f32_e32 v64, v64, v188
	v_mul_f32_e32 v67, v201, v201
	v_mul_f32_e32 v188, v203, v203
	v_fmac_f32_e32 v67, v200, v200
	v_fmac_f32_e32 v188, v202, v202
	v_add_f32_e32 v67, v67, v188
	v_add_f32_e32 v64, v64, v67
	ds_swizzle_b32 v67, v64 offset:swizzle(SWAP,16)
	v_cvt_pk_bf16_f32 v188, v200, v201
	v_cvt_pk_bf16_f32 v189, v202, v203
	global_store_dwordx4 v[234:235], v[200:203], off offset:528
	global_store_dwordx2 v[192:193], v[188:189], off offset:264
	s_waitcnt lgkmcnt(0)
	v_add_f32_e32 v64, v64, v67
	v_mov_b32_e32 v67, v64
	s_nop 1
	v_permlane32_swap_b32_e32 v64, v67
	s_and_saveexec_b64 s[10:11], s[4:5]
	s_cbranch_execz .LBB0_1096
	v_lshl_add_u64 v[188:189], v[228:229], 2, v[70:71]
	v_add_f32_e32 v64, v64, v67
	v_mov_b32_e32 v225, v64

; __device__ __forceinline__ unsigned cvtpk(float lo, float hi) { f32x2 v = {lo, hi}; bf16x2_t b = __builtin_convertvector(v, bf16x2_t); return __builtin_bit_cast(unsigned, b); }
; #define SWZ_XOR(v, m) __uint_as_float((unsigned)__builtin_amdgcn_ds_swizzle((int)__float_as_uint(v), ((m) << 10) | 0x1f))
; __device__ __forceinline__ float sum32x(float v) { auto rr = __builtin_amdgcn_permlane32_swap(__float_as_uint(v), __float_as_uint(v), false, false); return __uint_as_float(rr[0]) + __uint_as_float(rr[1]); }
;     __device__ __forceinline__ void operator()(const pg8::f32x4 (&acc)[2][2][4][2], const pg8::Unit& u, int wr, int wc, int fr, int fq) const {
;     ...
;                 for (int m = 0; m < 4; ++m) {
;                     const size_t ro = (size_t)(rowb + 128 * ai + 16 * m) * ldc + colb;
;                     float ssr = 0.f;
; #pragma unroll
;                     for (int bj = 0; bj < 2; ++bj)
; #pragma unroll
;                         for (int n = 0; n < 2; ++n) {
;                             const size_t off = ro + 128 * bj + NS * n;
;                             const pg8::f32x4 v = pre[m][bj][n] + acc[ai][bj][m][n] * coef;
;                             *(pg8::f32x4*)(fout + off) = v;
;                             if (flags & 2) { u32x2 w; w.x = cvtpk(v[0], v[1]); w.y = cvtpk(v[2], v[3]); *(u32x2*)(o0 + off) = w; ssr += (v[0] * v[0] + v[1] * v[1]) + (v[2] * v[2] + v[3] * v[3]); }
;                         }
;                     if (flags & 2) { ssr += SWZ_XOR(ssr, 16); ssr = sum32x(ssr); if (fq == 0) atomicAdd((float*)o1 + (rowb + 128 * ai + 16 * m), ssr); }
;                 }
.LBB0_1099:
	v_lshl_add_u64 v[190:191], v[240:241], 0, v[230:231]
	v_mov_b32_e32 v67, v66
	s_waitcnt vmcnt(11)
	v_pk_fma_f32 v[196:197], v[46:47], v[66:67], v[186:187]
	v_pk_fma_f32 v[194:195], v[44:45], v[232:233], v[184:185]
	v_lshl_add_u64 v[198:199], v[190:191], 2, v[138:139]
	s_mov_b64 s[10:11], -1
	s_and_b64 vcc, exec, s[8:9]
	v_pk_fma_f32 v[192:193], v[36:37], v[232:233], v[180:181]
	s_waitcnt vmcnt(9)
	v_pk_fma_f32 v[188:189], v[40:41], v[232:233], v[176:177]
	v_pk_fma_f32 v[184:185], v[32:33], v[232:233], v[172:173]
	global_store_dwordx4 v[198:199], v[194:197], off
	s_cbranch_vccnz .LBB0_1103
	v_cvt_pk_bf16_f32 v172, v194, v195
	v_cvt_pk_bf16_f32 v173, v196, v197
	v_lshl_add_u64 v[176:177], v[190:191], 1, v[68:69]
	global_store_dwordx2 v[176:177], v[172:173], off
	v_mul_f32_e32 v64, v195, v195
	v_mul_f32_e32 v172, v197, v197
	v_fmac_f32_e32 v64, v194, v194
	v_fmac_f32_e32 v172, v196, v196
	v_pk_fma_f32 v[194:195], v[38:39], v[66:67], v[182:183]
	v_add_f32_e32 v64, v64, v172
	v_cvt_pk_bf16_f32 v172, v192, v193
	v_cvt_pk_bf16_f32 v173, v194, v195
	global_store_dwordx4 v[198:199], v[192:195], off offset:16
	global_store_dwordx2 v[176:177], v[172:173], off offset:8
	v_mul_f32_e32 v172, v193, v193
	v_mul_f32_e32 v173, v195, v195
	v_fmac_f32_e32 v172, v192, v192
	v_fmac_f32_e32 v173, v194, v194
	v_add_f32_e32 v172, v172, v173
	v_pk_fma_f32 v[190:191], v[42:43], v[66:67], v[178:179]
	v_add_f32_e32 v64, v64, v172
	v_cvt_pk_bf16_f32 v172, v188, v189
	v_cvt_pk_bf16_f32 v173, v190, v191
	global_store_dwordx4 v[198:199], v[188:191], off offset:512
	global_store_dwordx2 v[176:177], v[172:173], off offset:256
	v_mul_f32_e32 v172, v189, v189
	v_mul_f32_e32 v173, v191, v191
	v_fmac_f32_e32 v172, v188, v188
	v_fmac_f32_e32 v173, v190, v190
	v_add_f32_e32 v172, v172, v173
	v_pk_fma_f32 v[186:187], v[34:35], v[66:67], v[174:175]
	v_add_f32_e32 v64, v64, v172
	v_mul_f32_e32 v67, v185, v185
	v_mul_f32_e32 v172, v187, v187
	v_fmac_f32_e32 v67, v184, v184
	v_fmac_f32_e32 v172, v186, v186
	v_add_f32_e32 v67, v67, v172
	v_add_f32_e32 v64, v64, v67
	ds_swizzle_b32 v67, v64 offset:swizzle(SWAP,16)
	v_cvt_pk_bf16_f32 v172, v184, v185
	v_cvt_pk_bf16_f32 v173, v186, v187
	global_store_dwordx4 v[198:199], v[184:187], off offset:528
	global_store_dwordx2 v[176:177], v[172:173], off offset:264
	s_waitcnt lgkmcnt(0)
	v_add_f32_e32 v64, v64, v67
	v_mov_b32_e32 v67, v64
	s_nop 1
	v_permlane32_swap_b32_e32 v64, v67
	s_and_saveexec_b64 s[10:11], s[4:5]
	s_cbranch_execz .LBB0_1102
	v_lshl_add_u64 v[172:173], v[228:229], 2, v[70:71]
	v_add_f32_e32 v64, v64, v67
	v_mov_b32_e32 v227, v64

; __device__ __forceinline__ unsigned cvtpk(float lo, float hi) { f32x2 v = {lo, hi}; bf16x2_t b = __builtin_convertvector(v, bf16x2_t); return __builtin_bit_cast(unsigned, b); }
; #define SWZ_XOR(v, m) __uint_as_float((unsigned)__builtin_amdgcn_ds_swizzle((int)__float_as_uint(v), ((m) << 10) | 0x1f))
; __device__ __forceinline__ float sum32x(float v) { auto rr = __builtin_amdgcn_permlane32_swap(__float_as_uint(v), __float_as_uint(v), false, false); return __uint_as_float(rr[0]) + __uint_as_float(rr[1]); }
;     __device__ __forceinline__ void operator()(const pg8::f32x4 (&acc)[2][2][4][2], const pg8::Unit& u, int wr, int wc, int fr, int fq) const {
;     ...
;                 for (int m = 0; m < 4; ++m) {
;                     const size_t ro = (size_t)(rowb + 128 * ai + 16 * m) * ldc + colb;
;                     float ssr = 0.f;
; #pragma unroll
;                     for (int bj = 0; bj < 2; ++bj)
; #pragma unroll
;                         for (int n = 0; n < 2; ++n) {
;                             const size_t off = ro + 128 * bj + NS * n;
;                             const pg8::f32x4 v = pre[m][bj][n] + acc[ai][bj][m][n] * coef;
;                             *(pg8::f32x4*)(fout + off) = v;
;                             if (flags & 2) { u32x2 w; w.x = cvtpk(v[0], v[1]); w.y = cvtpk(v[2], v[3]); *(u32x2*)(o0 + off) = w; ssr += (v[0] * v[0] + v[1] * v[1]) + (v[2] * v[2] + v[3] * v[3]); }
;                         }
;                     if (flags & 2) { ssr += SWZ_XOR(ssr, 16); ssr = sum32x(ssr); if (fq == 0) atomicAdd((float*)o1 + (rowb + 128 * ai + 16 * m), ssr); }
;                 }
.LBB0_1105:
	v_lshl_add_u64 v[174:175], v[238:239], 0, v[230:231]
	v_mov_b32_e32 v67, v66
	s_waitcnt vmcnt(8)
	v_pk_fma_f32 v[180:181], v[30:31], v[66:67], v[170:171]
	v_pk_fma_f32 v[178:179], v[28:29], v[232:233], v[168:169]
	v_lshl_add_u64 v[182:183], v[174:175], 2, v[138:139]
	s_mov_b64 s[10:11], -1
	s_and_b64 vcc, exec, s[8:9]
	v_pk_fma_f32 v[176:177], v[20:21], v[232:233], v[164:165]
	s_waitcnt vmcnt(6)
	v_pk_fma_f32 v[172:173], v[24:25], v[232:233], v[160:161]
	v_pk_fma_f32 v[168:169], v[16:17], v[232:233], v[156:157]
	global_store_dwordx4 v[182:183], v[178:181], off
	s_cbranch_vccnz .LBB0_1109
	v_cvt_pk_bf16_f32 v156, v178, v179
	v_cvt_pk_bf16_f32 v157, v180, v181
	v_lshl_add_u64 v[160:161], v[174:175], 1, v[68:69]
	global_store_dwordx2 v[160:161], v[156:157], off
	v_mul_f32_e32 v64, v179, v179
	v_mul_f32_e32 v156, v181, v181
	v_fmac_f32_e32 v64, v178, v178
	v_fmac_f32_e32 v156, v180, v180
	v_pk_fma_f32 v[178:179], v[22:23], v[66:67], v[166:167]
	v_add_f32_e32 v64, v64, v156
	v_cvt_pk_bf16_f32 v156, v176, v177
	v_cvt_pk_bf16_f32 v157, v178, v179
	global_store_dwordx4 v[182:183], v[176:179], off offset:16
	global_store_dwordx2 v[160:161], v[156:157], off offset:8
	v_mul_f32_e32 v156, v177, v177
	v_mul_f32_e32 v157, v179, v179
	v_fmac_f32_e32 v156, v176, v176
	v_fmac_f32_e32 v157, v178, v178
	v_add_f32_e32 v156, v156, v157
	v_pk_fma_f32 v[174:175], v[26:27], v[66:67], v[162:163]
	v_add_f32_e32 v64, v64, v156
	v_cvt_pk_bf16_f32 v156, v172, v173
	v_cvt_pk_bf16_f32 v157, v174, v175
	global_store_dwordx4 v[182:183], v[172:175], off offset:512
	global_store_dwordx2 v[160:161], v[156:157], off offset:256
	v_mul_f32_e32 v156, v173, v173
	v_mul_f32_e32 v157, v175, v175
	v_fmac_f32_e32 v156, v172, v172
	v_fmac_f32_e32 v157, v174, v174
	v_add_f32_e32 v156, v156, v157
	v_pk_fma_f32 v[170:171], v[18:19], v[66:67], v[158:159]
	v_add_f32_e32 v64, v64, v156
	v_mul_f32_e32 v67, v169, v169
	v_mul_f32_e32 v156, v171, v171
	v_fmac_f32_e32 v67, v168, v168
	v_fmac_f32_e32 v156, v170, v170
	v_add_f32_e32 v67, v67, v156
	v_add_f32_e32 v64, v64, v67
	ds_swizzle_b32 v67, v64 offset:swizzle(SWAP,16)
	v_cvt_pk_bf16_f32 v156, v168, v169
	v_cvt_pk_bf16_f32 v157, v170, v171
	global_store_dwordx4 v[182:183], v[168:171], off offset:528
	global_store_dwordx2 v[160:161], v[156:157], off offset:264
	s_waitcnt lgkmcnt(0)
	v_add_f32_e32 v64, v64, v67
	v_mov_b32_e32 v67, v64
	s_nop 1
	v_permlane32_swap_b32_e32 v64, v67
	s_and_saveexec_b64 s[10:11], s[4:5]
	s_cbranch_execz .LBB0_1108
	v_lshl_add_u64 v[156:157], v[228:229], 2, v[70:71]
	v_add_f32_e32 v64, v64, v67
	v_mov_b32_e32 v214, v64

; __device__ __forceinline__ unsigned cvtpk(float lo, float hi) { f32x2 v = {lo, hi}; bf16x2_t b = __builtin_convertvector(v, bf16x2_t); return __builtin_bit_cast(unsigned, b); }
; #define SWZ_XOR(v, m) __uint_as_float((unsigned)__builtin_amdgcn_ds_swizzle((int)__float_as_uint(v), ((m) << 10) | 0x1f))
; __device__ __forceinline__ float sum32x(float v) { auto rr = __builtin_amdgcn_permlane32_swap(__float_as_uint(v), __float_as_uint(v), false, false); return __uint_as_float(rr[0]) + __uint_as_float(rr[1]); }
;     __device__ __forceinline__ void operator()(const pg8::f32x4 (&acc)[2][2][4][2], const pg8::Unit& u, int wr, int wc, int fr, int fq) const {
;     ...
;                 for (int m = 0; m < 4; ++m) {
;                     const size_t ro = (size_t)(rowb + 128 * ai + 16 * m) * ldc + colb;
;                     float ssr = 0.f;
; #pragma unroll
;                     for (int bj = 0; bj < 2; ++bj)
; #pragma unroll
;                         for (int n = 0; n < 2; ++n) {
;                             const size_t off = ro + 128 * bj + NS * n;
;                             const pg8::f32x4 v = pre[m][bj][n] + acc[ai][bj][m][n] * coef;
;                             *(pg8::f32x4*)(fout + off) = v;
;                             if (flags & 2) { u32x2 w; w.x = cvtpk(v[0], v[1]); w.y = cvtpk(v[2], v[3]); *(u32x2*)(o0 + off) = w; ssr += (v[0] * v[0] + v[1] * v[1]) + (v[2] * v[2] + v[3] * v[3]); }
;                         }
;                     if (flags & 2) { ssr += SWZ_XOR(ssr, 16); ssr = sum32x(ssr); if (fq == 0) atomicAdd((float*)o1 + (rowb + 128 * ai + 16 * m), ssr); }
;                 }
.LBB0_1111:
	v_lshl_add_u64 v[164:165], v[236:237], 0, v[230:231]
	v_mov_b32_e32 v67, v66
	s_waitcnt vmcnt(5)
	v_pk_fma_f32 v[160:161], v[14:15], v[66:67], v[154:155]
	v_pk_fma_f32 v[158:159], v[12:13], v[232:233], v[152:153]
	v_lshl_add_u64 v[162:163], v[164:165], 2, v[138:139]
	s_mov_b64 s[10:11], -1
	s_and_b64 vcc, exec, s[8:9]
	v_pk_fma_f32 v[156:157], v[4:5], v[232:233], v[148:149]
	s_waitcnt vmcnt(3)
	v_pk_fma_f32 v[152:153], v[8:9], v[232:233], v[144:145]
	v_pk_fma_f32 v[138:139], v[0:1], v[232:233], v[140:141]
	global_store_dwordx4 v[162:163], v[158:161], off
	s_cbranch_vccnz .LBB0_1115
	v_cvt_pk_bf16_f32 v140, v158, v159
	v_cvt_pk_bf16_f32 v141, v160, v161
	v_lshl_add_u64 v[144:145], v[164:165], 1, v[68:69]
	global_store_dwordx2 v[144:145], v[140:141], off
	v_mul_f32_e32 v64, v159, v159
	v_mul_f32_e32 v140, v161, v161
	v_fmac_f32_e32 v64, v158, v158
	v_fmac_f32_e32 v140, v160, v160
	v_pk_fma_f32 v[158:159], v[6:7], v[66:67], v[150:151]
	v_add_f32_e32 v64, v64, v140
	v_cvt_pk_bf16_f32 v140, v156, v157
	v_cvt_pk_bf16_f32 v141, v158, v159
	global_store_dwordx4 v[162:163], v[156:159], off offset:16
	global_store_dwordx2 v[144:145], v[140:141], off offset:8
	v_mul_f32_e32 v140, v157, v157
	v_mul_f32_e32 v141, v159, v159
	v_fmac_f32_e32 v140, v156, v156
	v_fmac_f32_e32 v141, v158, v158
	v_add_f32_e32 v140, v140, v141
	v_pk_fma_f32 v[154:155], v[10:11], v[66:67], v[146:147]
	v_add_f32_e32 v64, v64, v140
	v_cvt_pk_bf16_f32 v140, v152, v153
	v_cvt_pk_bf16_f32 v141, v154, v155
	global_store_dwordx4 v[162:163], v[152:155], off offset:512
	global_store_dwordx2 v[144:145], v[140:141], off offset:256
	v_mul_f32_e32 v140, v153, v153
	v_mul_f32_e32 v141, v155, v155
	v_fmac_f32_e32 v140, v152, v152
	v_fmac_f32_e32 v141, v154, v154
	v_add_f32_e32 v140, v140, v141
	v_add_f32_e32 v64, v64, v140
	v_pk_fma_f32 v[140:141], v[2:3], v[66:67], v[142:143]
	v_mul_f32_e32 v67, v139, v139
	v_mul_f32_e32 v148, v141, v141
	v_fmac_f32_e32 v67, v138, v138
	v_fmac_f32_e32 v148, v140, v140
	v_add_f32_e32 v67, v67, v148
	v_add_f32_e32 v64, v64, v67
	ds_swizzle_b32 v67, v64 offset:swizzle(SWAP,16)
	v_cvt_pk_bf16_f32 v148, v138, v139
	v_cvt_pk_bf16_f32 v149, v140, v141
	global_store_dwordx4 v[162:163], v[138:141], off offset:528
	global_store_dwordx2 v[144:145], v[148:149], off offset:264
	s_waitcnt lgkmcnt(0)
	v_add_f32_e32 v64, v64, v67
	v_mov_b32_e32 v67, v64
	s_nop 1
	v_permlane32_swap_b32_e32 v64, v67
	s_and_saveexec_b64 s[8:9], s[4:5]
	s_cbranch_execz .LBB0_1114
	v_lshl_add_u64 v[70:71], v[228:229], 2, v[70:71]
	v_add_f32_e32 v64, v64, v67
	global_atomic_add_f32 v[70:71], v64, off offset:704
	global_atomic_add_f32 v[70:71], v217, off
	global_atomic_add_f32 v[70:71], v219, off offset:64
	global_atomic_add_f32 v[70:71], v221, off offset:128
	global_atomic_add_f32 v[70:71], v223, off offset:192
	global_atomic_add_f32 v[70:71], v225, off offset:512
	global_atomic_add_f32 v[70:71], v227, off offset:576
	global_atomic_add_f32 v[70:71], v214, off offset:640

; __device__ __forceinline__ unsigned cvtpk(float lo, float hi) { f32x2 v = {lo, hi}; bf16x2_t b = __builtin_convertvector(v, bf16x2_t); return __builtin_bit_cast(unsigned, b); }
; #define SWZ_XOR(v, m) __uint_as_float((unsigned)__builtin_amdgcn_ds_swizzle((int)__float_as_uint(v), ((m) << 10) | 0x1f))
; __device__ __forceinline__ float sum32x(float v) { auto rr = __builtin_amdgcn_permlane32_swap(__float_as_uint(v), __float_as_uint(v), false, false); return __uint_as_float(rr[0]) + __uint_as_float(rr[1]); }
;     __device__ __forceinline__ void operator()(const pg8::f32x4 (&acc)[2][2][4][2], const pg8::Unit& u, int wr, int wc, int fr, int fq) const {
;     ...
;                 for (int m = 0; m < 4; ++m) {
;                     const size_t ro = (size_t)(rowb + 128 * ai + 16 * m) * ldc + colb;
;                     float ssr = 0.f;
; #pragma unroll
;                     for (int bj = 0; bj < 2; ++bj)
; #pragma unroll
;                         for (int n = 0; n < 2; ++n) {
;                             const size_t off = ro + 128 * bj + NS * n;
;                             const pg8::f32x4 v = pre[m][bj][n] + acc[ai][bj][m][n] * coef;
;                             *(pg8::f32x4*)(fout + off) = v;
;                             if (flags & 2) { u32x2 w; w.x = cvtpk(v[0], v[1]); w.y = cvtpk(v[2], v[3]); *(u32x2*)(o0 + off) = w; ssr += (v[0] * v[0] + v[1] * v[1]) + (v[2] * v[2] + v[3] * v[3]); }
;                         }
;                     if (flags & 2) { ssr += SWZ_XOR(ssr, 16); ssr = sum32x(ssr); if (fq == 0) atomicAdd((float*)o1 + (rowb + 128 * ai + 16 * m), ssr); }
;                 }
.LBB0_1191:
	v_lshl_add_u64 v[190:191], v[240:241], 0, v[230:231]
	v_mov_b32_e32 v67, v66
	v_cndmask_b32_e64 v64, 0, 1, s[10:11]
	s_waitcnt vmcnt(11)
	v_pk_fma_f32 v[196:197], v[118:119], v[66:67], v[186:187]
	v_pk_fma_f32 v[194:195], v[116:117], v[232:233], v[184:185]
	v_lshl_add_u64 v[198:199], v[190:191], 2, v[138:139]
	s_mov_b64 s[56:57], -1
	v_cmp_ne_u32_e64 s[8:9], 1, v64
	s_andn2_b64 vcc, exec, s[10:11]
	v_pk_fma_f32 v[192:193], v[108:109], v[232:233], v[180:181]
	s_waitcnt vmcnt(9)
	v_pk_fma_f32 v[188:189], v[112:113], v[232:233], v[176:177]
	v_pk_fma_f32 v[184:185], v[104:105], v[232:233], v[172:173]
	global_store_dwordx4 v[198:199], v[194:197], off
	s_cbranch_vccnz .LBB0_1195
	v_cvt_pk_bf16_f32 v172, v194, v195
	v_cvt_pk_bf16_f32 v173, v196, v197
	v_lshl_add_u64 v[176:177], v[190:191], 1, v[68:69]
	global_store_dwordx2 v[176:177], v[172:173], off
	v_mul_f32_e32 v64, v195, v195
	v_mul_f32_e32 v172, v197, v197
	v_fmac_f32_e32 v64, v194, v194
	v_fmac_f32_e32 v172, v196, v196
	v_pk_fma_f32 v[194:195], v[110:111], v[66:67], v[182:183]
	v_add_f32_e32 v64, v64, v172
	v_cvt_pk_bf16_f32 v172, v192, v193
	v_cvt_pk_bf16_f32 v173, v194, v195
	global_store_dwordx4 v[198:199], v[192:195], off offset:16
	global_store_dwordx2 v[176:177], v[172:173], off offset:8
	v_mul_f32_e32 v172, v193, v193
	v_mul_f32_e32 v173, v195, v195
	v_fmac_f32_e32 v172, v192, v192
	v_fmac_f32_e32 v173, v194, v194
	v_add_f32_e32 v172, v172, v173
	v_pk_fma_f32 v[190:191], v[114:115], v[66:67], v[178:179]
	v_add_f32_e32 v64, v64, v172
	v_cvt_pk_bf16_f32 v172, v188, v189
	v_cvt_pk_bf16_f32 v173, v190, v191
	global_store_dwordx4 v[198:199], v[188:191], off offset:512
	global_store_dwordx2 v[176:177], v[172:173], off offset:256
	v_mul_f32_e32 v172, v189, v189
	v_mul_f32_e32 v173, v191, v191
	v_fmac_f32_e32 v172, v188, v188
	v_fmac_f32_e32 v173, v190, v190
	v_add_f32_e32 v172, v172, v173
	v_pk_fma_f32 v[186:187], v[106:107], v[66:67], v[174:175]
	v_add_f32_e32 v64, v64, v172
	v_mul_f32_e32 v67, v185, v185
	v_mul_f32_e32 v172, v187, v187
	v_fmac_f32_e32 v67, v184, v184
	v_fmac_f32_e32 v172, v186, v186
	v_add_f32_e32 v67, v67, v172
	v_add_f32_e32 v64, v64, v67
	ds_swizzle_b32 v67, v64 offset:swizzle(SWAP,16)
	v_cvt_pk_bf16_f32 v172, v184, v185
	v_cvt_pk_bf16_f32 v173, v186, v187
	global_store_dwordx4 v[198:199], v[184:187], off offset:528
	global_store_dwordx2 v[176:177], v[172:173], off offset:264
	s_waitcnt lgkmcnt(0)
	v_add_f32_e32 v64, v64, v67
	v_mov_b32_e32 v67, v64
	s_nop 1
	v_permlane32_swap_b32_e32 v64, v67
	s_and_saveexec_b64 s[10:11], s[4:5]
	s_cbranch_execz .LBB0_1194
	v_lshl_add_u64 v[172:173], v[228:229], 2, v[70:71]
	v_add_f32_e32 v64, v64, v67
	v_mov_b32_e32 v219, v64
